# v9 plus SwiGLU GEMM epilogue: eight row-scale loads issued together with one wait instead of eight load-wait round trips
# speedup vs baseline: 1.0062x; 1.0009x over previous
; __device__ __forceinline__ float rs_of(float ss, float invn) { return rsqrtf(ss * invn + EPS); }
; __device__ __forceinline__ float sigmoidf_(float v) { return __builtin_amdgcn_rcpf(1.f + __expf(-v)); }
;     __device__ __forceinline__ float rowscale(int row) const { return rs_of(ss[row], 1.f / DM); }
;     __device__ __forceinline__ float rowscale(int row) const { return rs_of(ssmem[row], 1.f / DM); }
;     __device__ __forceinline__ float rowscale(int row) const { return rs_of(qss[row * 4 + h], 1.f / 256) * c; }
;     __device__ __forceinline__ float rowscale(int row) const { return 1.f / __hip_atomic_load(lsum + row * 4 + h, __ATOMIC_RELAXED, __HIP_MEMORY_SCOPE_AGENT); }
;     __device__ __forceinline__ float rowscale(int row) const { return rs_of(ss[row], 1.f / DM); }
;     __device__ __forceinline__ void apply2(int row, int lcol0, f32x4 a0, f32x4 a1, f32x4 b0, f32x4 b1, float rs) const {
; #pragma unroll
;         for (int i = 0; i < 4; ++i) {
;             const float x = a0[i] * rs, y = a1[i] * rs;
;             a0[i] = x * sigmoidf_(x) * (b0[i] * rs); a1[i] = y * sigmoidf_(y) * (b1[i] * rs);
;         }
;     __device__ __forceinline__ void operator()(f32x4 (&acc)[2][2][4][2], const Unit& u, int wr, int wc, int fr, int fq) const {
;     ...
;         float rsv[2][4];
; #pragma unroll
;         for (int ai = 0; ai < 2; ++ai)
; #pragma unroll
;             for (int m = 0; m < 4; ++m) rsv[ai][m] = f.rowscale(u.pm * BM + ai * HALF + wr * 64 + m * 16 + fr);
.LBB1_90:
	s_lshl_b32 s37, s56, 8
	v_add_u32_e32 v140, s37, v145
	v_ashrrev_i32_e32 v141, 31, v140
	v_lshl_add_u64 v[142:143], v[140:141], 2, s[8:9]
	flat_load_dword v230, v[142:143]
	flat_load_dword v231, v[142:143] offset:64
	flat_load_dword v232, v[142:143] offset:128
	flat_load_dword v233, v[142:143] offset:192
	flat_load_dword v234, v[142:143] offset:512
	flat_load_dword v235, v[142:143] offset:576
	flat_load_dword v236, v[142:143] offset:640
	flat_load_dword v237, v[142:143] offset:704
	v_lshl_or_b32 v158, s52, 7, v155
	v_ashrrev_i32_e32 v159, 31, v158
	s_mov_b64 s[52:53], -1
	s_waitcnt vmcnt(0) lgkmcnt(0)
	v_fmamk_f32 v141, v230, 0x3a000000, v250
	v_cmp_gt_f32_e32 vcc, s3, v141
	v_mul_f32_e32 v144, 0x4b800000, v141
	s_nop 0
	v_cndmask_b32_e32 v141, v141, v144, vcc
	v_rsq_f32_e32 v141, v141
	s_nop 0
	v_mul_f32_e32 v144, 0x45800000, v141
	v_cndmask_b32_e32 v156, v141, v144, vcc
	v_pk_mul_f32 v[126:127], v[126:127], v[156:157] op_sel_hi:[1,0]
	v_pk_mul_f32 v[122:123], v[122:123], v[156:157] op_sel_hi:[1,0]
	v_pk_mul_f32 v[118:119], v[118:119], v[156:157] op_sel_hi:[1,0]
	v_pk_mul_f32 v[114:115], v[114:115], v[156:157] op_sel_hi:[1,0]
	v_pk_mul_f32 v[124:125], v[124:125], v[156:157] op_sel_hi:[1,0]
	v_pk_mul_f32 v[116:117], v[116:117], v[156:157] op_sel_hi:[1,0]
	v_fmamk_f32 v141, v231, 0x3a000000, v250
	v_cmp_gt_f32_e32 vcc, s3, v141
	v_mul_f32_e32 v144, 0x4b800000, v141
	s_nop 0
	v_cndmask_b32_e32 v141, v141, v144, vcc
	v_rsq_f32_e32 v141, v141
	s_nop 0
	v_mul_f32_e32 v144, 0x45800000, v141
	v_cndmask_b32_e32 v154, v141, v144, vcc
	v_pk_mul_f32 v[110:111], v[110:111], v[154:155] op_sel_hi:[1,0]
	v_pk_mul_f32 v[102:103], v[102:103], v[154:155] op_sel_hi:[1,0]
	v_pk_mul_f32 v[106:107], v[106:107], v[154:155] op_sel_hi:[1,0]
	v_pk_mul_f32 v[98:99], v[98:99], v[154:155] op_sel_hi:[1,0]
	v_pk_mul_f32 v[104:105], v[104:105], v[154:155] op_sel_hi:[1,0]
	v_pk_mul_f32 v[100:101], v[100:101], v[154:155] op_sel_hi:[1,0]
	v_fmamk_f32 v141, v232, 0x3a000000, v250
	v_cmp_gt_f32_e32 vcc, s3, v141
	v_mul_f32_e32 v144, 0x4b800000, v141
	s_nop 0
	v_cndmask_b32_e32 v141, v141, v144, vcc
	v_rsq_f32_e32 v141, v141
	s_nop 0
	v_mul_f32_e32 v144, 0x45800000, v141
	v_cndmask_b32_e32 v152, v141, v144, vcc
	v_pk_mul_f32 v[94:95], v[94:95], v[152:153] op_sel_hi:[1,0]
	v_pk_mul_f32 v[86:87], v[86:87], v[152:153] op_sel_hi:[1,0]
	v_pk_mul_f32 v[90:91], v[90:91], v[152:153] op_sel_hi:[1,0]
	v_pk_mul_f32 v[82:83], v[82:83], v[152:153] op_sel_hi:[1,0]
	v_pk_mul_f32 v[88:89], v[88:89], v[152:153] op_sel_hi:[1,0]
	v_pk_mul_f32 v[84:85], v[84:85], v[152:153] op_sel_hi:[1,0]
	v_fmamk_f32 v141, v233, 0x3a000000, v250
	v_cmp_gt_f32_e32 vcc, s3, v141
	v_mul_f32_e32 v144, 0x4b800000, v141
	s_nop 0
	v_cndmask_b32_e32 v141, v141, v144, vcc
	v_rsq_f32_e32 v141, v141
	s_nop 0
	v_mul_f32_e32 v144, 0x45800000, v141
	v_cndmask_b32_e32 v150, v141, v144, vcc
	v_pk_mul_f32 v[78:79], v[78:79], v[150:151] op_sel_hi:[1,0]
	v_pk_mul_f32 v[70:71], v[70:71], v[150:151] op_sel_hi:[1,0]
	v_pk_mul_f32 v[74:75], v[74:75], v[150:151] op_sel_hi:[1,0]
	v_pk_mul_f32 v[66:67], v[66:67], v[150:151] op_sel_hi:[1,0]
	v_pk_mul_f32 v[72:73], v[72:73], v[150:151] op_sel_hi:[1,0]
	v_pk_mul_f32 v[68:69], v[68:69], v[150:151] op_sel_hi:[1,0]
	v_fmamk_f32 v141, v234, 0x3a000000, v250
	v_cmp_gt_f32_e32 vcc, s3, v141
	v_mul_f32_e32 v144, 0x4b800000, v141
	s_nop 0
	v_cndmask_b32_e32 v141, v141, v144, vcc
	v_rsq_f32_e32 v141, v141
	s_nop 0
	v_mul_f32_e32 v144, 0x45800000, v141
	v_cndmask_b32_e32 v148, v141, v144, vcc
	v_pk_mul_f32 v[62:63], v[62:63], v[148:149] op_sel_hi:[1,0]
	v_pk_mul_f32 v[54:55], v[54:55], v[148:149] op_sel_hi:[1,0]
	v_pk_mul_f32 v[58:59], v[58:59], v[148:149] op_sel_hi:[1,0]
	v_pk_mul_f32 v[50:51], v[50:51], v[148:149] op_sel_hi:[1,0]
	v_pk_mul_f32 v[56:57], v[56:57], v[148:149] op_sel_hi:[1,0]
	v_pk_mul_f32 v[52:53], v[52:53], v[148:149] op_sel_hi:[1,0]
	v_fmamk_f32 v141, v235, 0x3a000000, v250
	v_cmp_gt_f32_e32 vcc, s3, v141
	v_mul_f32_e32 v144, 0x4b800000, v141
	s_nop 0
	v_cndmask_b32_e32 v141, v141, v144, vcc
	v_rsq_f32_e32 v141, v141
	s_nop 0
	v_mul_f32_e32 v144, 0x45800000, v141
	v_cndmask_b32_e32 v146, v141, v144, vcc
	v_pk_mul_f32 v[46:47], v[46:47], v[146:147] op_sel_hi:[1,0]
	v_pk_mul_f32 v[38:39], v[38:39], v[146:147] op_sel_hi:[1,0]
	v_pk_mul_f32 v[42:43], v[42:43], v[146:147] op_sel_hi:[1,0]
	v_pk_mul_f32 v[34:35], v[34:35], v[146:147] op_sel_hi:[1,0]
	v_pk_mul_f32 v[40:41], v[40:41], v[146:147] op_sel_hi:[1,0]
	v_pk_mul_f32 v[36:37], v[36:37], v[146:147] op_sel_hi:[1,0]
	v_fmamk_f32 v141, v236, 0x3a000000, v250
	v_cmp_gt_f32_e32 vcc, s3, v141
	v_mul_f32_e32 v144, 0x4b800000, v141
	s_nop 0
	v_cndmask_b32_e32 v141, v141, v144, vcc
	v_rsq_f32_e32 v141, v141
	s_nop 0
	v_mul_f32_e32 v144, 0x45800000, v141
	v_cndmask_b32_e32 v144, v141, v144, vcc
	v_pk_mul_f32 v[30:31], v[30:31], v[144:145] op_sel_hi:[1,0]
	v_pk_mul_f32 v[22:23], v[22:23], v[144:145] op_sel_hi:[1,0]
	v_pk_mul_f32 v[26:27], v[26:27], v[144:145] op_sel_hi:[1,0]
	v_pk_mul_f32 v[18:19], v[18:19], v[144:145] op_sel_hi:[1,0]
	v_pk_mul_f32 v[24:25], v[24:25], v[144:145] op_sel_hi:[1,0]
	v_pk_mul_f32 v[20:21], v[20:21], v[144:145] op_sel_hi:[1,0]
	v_fmamk_f32 v141, v237, 0x3a000000, v250
	v_cmp_gt_f32_e32 vcc, s3, v141
	v_mul_f32_e32 v142, 0x4b800000, v141
	s_nop 0
	v_cndmask_b32_e32 v141, v141, v142, vcc
	v_rsq_f32_e32 v141, v141
	s_nop 0
	v_mul_f32_e32 v142, 0x45800000, v141
	v_cndmask_b32_e32 v142, v141, v142, vcc
	v_mul_f32_e32 v141, 0xbfb8aa3b, v126
	v_exp_f32_e32 v141, v141
	v_pk_mul_f32 v[14:15], v[14:15], v[142:143] op_sel_hi:[1,0]
	v_pk_mul_f32 v[6:7], v[6:7], v[142:143] op_sel_hi:[1,0]
; __device__ __forceinline__ u32x4 pack8(f32x4 a, f32x4 b) { u32x4 w; w.x = pk2(a.x, a.y); w.y = pk2(a.z, a.w); w.z = pk2(b.x, b.y); w.w = pk2(b.z, b.w); return w; }
; __device__ __forceinline__ float sigmoidf_(float v) { return __builtin_amdgcn_rcpf(1.f + __expf(-v)); }
;     __device__ __forceinline__ void apply2(int row, int lcol0, f32x4 a0, f32x4 a1, f32x4 b0, f32x4 b1, float rs) const {
; #pragma unroll
;         for (int i = 0; i < 4; ++i) {
;             const float x = a0[i] * rs, y = a1[i] * rs;
;             a0[i] = x * sigmoidf_(x) * (b0[i] * rs); a1[i] = y * sigmoidf_(y) * (b1[i] * rs);
;         }
;         *(u32x4*)(H + (size_t)row * DFF + lcol0) = pack8(a0, a1);
;     }
	v_pk_mul_f32 v[10:11], v[10:11], v[142:143] op_sel_hi:[1,0]
	v_add_f32_e32 v141, 1.0, v141
	v_rcp_f32_e32 v160, v141
	v_mul_f32_e32 v141, 0xbfb8aa3b, v127
	v_exp_f32_e32 v141, v141
	v_pk_mul_f32 v[2:3], v[2:3], v[142:143] op_sel_hi:[1,0]
	v_pk_mul_f32 v[8:9], v[8:9], v[142:143] op_sel_hi:[1,0]
	v_pk_mul_f32 v[4:5], v[4:5], v[142:143] op_sel_hi:[1,0]
	v_add_f32_e32 v141, 1.0, v141
	v_rcp_f32_e32 v161, v141
	s_andn2_b64 vcc, exec, s[38:39]
	v_pk_mul_f32 v[126:127], v[126:127], v[160:161]
	s_nop 0
	v_pk_mul_f32 v[122:123], v[122:123], v[126:127]
	v_mul_f32_e32 v126, 0xbfb8aa3b, v118
	v_mul_f32_e32 v127, 0xbfb8aa3b, v119
	v_exp_f32_e32 v126, v126
	v_exp_f32_e32 v127, v127
	v_add_f32_e32 v126, 1.0, v126
	v_add_f32_e32 v127, 1.0, v127
	v_rcp_f32_e32 v126, v126
	v_rcp_f32_e32 v127, v127
	s_nop 0
	v_pk_mul_f32 v[118:119], v[118:119], v[126:127]
	s_nop 0
	v_pk_mul_f32 v[114:115], v[114:115], v[118:119]
	v_pk_mul_f32 v[118:119], v[128:129], v[156:157] op_sel_hi:[1,0]
	s_nop 0
	v_mul_f32_e32 v126, 0xbfb8aa3b, v118
	v_mul_f32_e32 v127, 0xbfb8aa3b, v119
	v_exp_f32_e32 v126, v126
	v_exp_f32_e32 v127, v127
	v_add_f32_e32 v126, 1.0, v126
	v_add_f32_e32 v127, 1.0, v127
	v_rcp_f32_e32 v126, v126
	v_rcp_f32_e32 v127, v127
	s_nop 0
	v_pk_mul_f32 v[118:119], v[118:119], v[126:127]
	s_nop 0
	v_pk_mul_f32 v[124:125], v[124:125], v[118:119]
	v_pk_mul_f32 v[118:119], v[120:121], v[156:157] op_sel_hi:[1,0]
	s_nop 0
	v_mul_f32_e32 v120, 0xbfb8aa3b, v118
	v_mul_f32_e32 v121, 0xbfb8aa3b, v119
	v_exp_f32_e32 v120, v120
	v_exp_f32_e32 v121, v121
	v_add_f32_e32 v120, 1.0, v120
	v_add_f32_e32 v121, 1.0, v121
	v_rcp_f32_e32 v120, v120
	v_rcp_f32_e32 v121, v121
	s_nop 0
	v_pk_mul_f32 v[118:119], v[118:119], v[120:121]
	s_nop 0
	v_pk_mul_f32 v[116:117], v[116:117], v[118:119]
	v_cvt_pk_bf16_f32 v120, v114, v115
	v_mov_b64_e32 v[114:115], s[6:7]
	v_cvt_pk_bf16_f32 v118, v122, v123
	v_cvt_pk_bf16_f32 v121, v116, v117
	v_mad_i64_i32 v[122:123], s[14:15], v140, s17, v[114:115]
	v_lshlrev_b64 v[116:117], 1, v[158:159]
	v_cvt_pk_bf16_f32 v119, v124, v125
	v_lshl_add_u64 v[122:123], v[122:123], 0, v[116:117]
	flat_store_dwordx4 v[122:123], v[118:121]
	s_nop 1
	v_mul_f32_e32 v118, 0xbfb8aa3b, v110
	v_mul_f32_e32 v119, 0xbfb8aa3b, v111
	v_exp_f32_e32 v118, v118
	v_exp_f32_e32 v119, v119
	v_add_u32_e32 v120, s37, v149
	v_add_f32_e32 v118, 1.0, v118
	v_add_f32_e32 v119, 1.0, v119
	v_rcp_f32_e32 v118, v118
	v_rcp_f32_e32 v119, v119
	s_nop 0
	v_pk_mul_f32 v[110:111], v[110:111], v[118:119]
	s_nop 0
	v_pk_mul_f32 v[102:103], v[102:103], v[110:111]
	v_mul_f32_e32 v110, 0xbfb8aa3b, v106
	v_mul_f32_e32 v111, 0xbfb8aa3b, v107
	v_exp_f32_e32 v110, v110
	v_exp_f32_e32 v111, v111
	v_add_f32_e32 v110, 1.0, v110
	v_add_f32_e32 v111, 1.0, v111
	v_rcp_f32_e32 v110, v110
	v_rcp_f32_e32 v111, v111
	s_nop 0
	v_pk_mul_f32 v[106:107], v[106:107], v[110:111]
	s_nop 0
	v_pk_mul_f32 v[106:107], v[98:99], v[106:107]
	v_pk_mul_f32 v[98:99], v[112:113], v[154:155] op_sel_hi:[1,0]
	s_nop 0
	v_mul_f32_e32 v110, 0xbfb8aa3b, v98
	v_mul_f32_e32 v111, 0xbfb8aa3b, v99
	v_exp_f32_e32 v110, v110
	v_exp_f32_e32 v111, v111
	v_add_f32_e32 v110, 1.0, v110
	v_add_f32_e32 v111, 1.0, v111
	v_rcp_f32_e32 v110, v110
	v_rcp_f32_e32 v111, v111
	s_nop 0
	v_pk_mul_f32 v[98:99], v[98:99], v[110:111]
	s_nop 0
	v_pk_mul_f32 v[104:105], v[104:105], v[98:99]
	v_pk_mul_f32 v[98:99], v[108:109], v[154:155] op_sel_hi:[1,0]
	s_nop 0
	v_mul_f32_e32 v108, 0xbfb8aa3b, v98
	v_mul_f32_e32 v109, 0xbfb8aa3b, v99
	v_exp_f32_e32 v108, v108
	v_exp_f32_e32 v109, v109
	v_add_f32_e32 v108, 1.0, v108
	v_add_f32_e32 v109, 1.0, v109
	v_rcp_f32_e32 v108, v108
	v_rcp_f32_e32 v109, v109
	s_nop 0
	v_pk_mul_f32 v[98:99], v[98:99], v[108:109]
	s_nop 0
	v_pk_mul_f32 v[108:109], v[100:101], v[98:99]
	v_cvt_pk_bf16_f32 v98, v102, v103
	v_mad_i64_i32 v[102:103], s[14:15], v120, s17, v[114:115]
	v_cvt_pk_bf16_f32 v99, v104, v105
	v_cvt_pk_bf16_f32 v100, v106, v107
	v_cvt_pk_bf16_f32 v101, v108, v109
	v_lshl_add_u64 v[102:103], v[102:103], 0, v[116:117]
	flat_store_dwordx4 v[102:103], v[98:101]
	s_nop 1
	v_mul_f32_e32 v98, 0xbfb8aa3b, v94
	v_mul_f32_e32 v99, 0xbfb8aa3b, v95
	v_exp_f32_e32 v98, v98
	v_exp_f32_e32 v99, v99
	v_add_u32_e32 v100, s37, v151
	v_add_f32_e32 v98, 1.0, v98
	v_add_f32_e32 v99, 1.0, v99
	v_rcp_f32_e32 v98, v98
	v_rcp_f32_e32 v99, v99
	s_nop 0
	v_pk_mul_f32 v[94:95], v[94:95], v[98:99]
	s_nop 0
	v_pk_mul_f32 v[86:87], v[86:87], v[94:95]
	v_mul_f32_e32 v94, 0xbfb8aa3b, v90
	v_mul_f32_e32 v95, 0xbfb8aa3b, v91
	v_exp_f32_e32 v94, v94
	v_exp_f32_e32 v95, v95
	v_add_f32_e32 v94, 1.0, v94
	v_add_f32_e32 v95, 1.0, v95
	v_rcp_f32_e32 v94, v94
	v_rcp_f32_e32 v95, v95
	s_nop 0
	v_pk_mul_f32 v[90:91], v[90:91], v[94:95]
	s_nop 0
	v_pk_mul_f32 v[90:91], v[82:83], v[90:91]
	v_pk_mul_f32 v[82:83], v[96:97], v[152:153] op_sel_hi:[1,0]
	s_nop 0
	v_mul_f32_e32 v94, 0xbfb8aa3b, v82
	v_mul_f32_e32 v95, 0xbfb8aa3b, v83
	v_exp_f32_e32 v94, v94
	v_exp_f32_e32 v95, v95
	v_add_f32_e32 v94, 1.0, v94
	v_add_f32_e32 v95, 1.0, v95
	v_rcp_f32_e32 v94, v94
	v_rcp_f32_e32 v95, v95
	s_nop 0
	v_pk_mul_f32 v[82:83], v[82:83], v[94:95]
	s_nop 0
	v_pk_mul_f32 v[88:89], v[88:89], v[82:83]
	v_pk_mul_f32 v[82:83], v[92:93], v[152:153] op_sel_hi:[1,0]
	s_nop 0
	v_mul_f32_e32 v92, 0xbfb8aa3b, v82
	v_mul_f32_e32 v93, 0xbfb8aa3b, v83
	v_exp_f32_e32 v92, v92
	v_exp_f32_e32 v93, v93
	v_add_f32_e32 v92, 1.0, v92
	v_add_f32_e32 v93, 1.0, v93
	v_rcp_f32_e32 v92, v92
	v_rcp_f32_e32 v93, v93
	s_nop 0
	v_pk_mul_f32 v[82:83], v[82:83], v[92:93]
	s_nop 0
	v_pk_mul_f32 v[92:93], v[84:85], v[82:83]
	v_cvt_pk_bf16_f32 v82, v86, v87
	v_mad_i64_i32 v[86:87], s[14:15], v100, s17, v[114:115]
; __device__ __forceinline__ u32x4 pack8(f32x4 a, f32x4 b) { u32x4 w; w.x = pk2(a.x, a.y); w.y = pk2(a.z, a.w); w.z = pk2(b.x, b.y); w.w = pk2(b.z, b.w); return w; }
; __device__ __forceinline__ float sigmoidf_(float v) { return __builtin_amdgcn_rcpf(1.f + __expf(-v)); }
;     __device__ __forceinline__ void apply2(int row, int lcol0, f32x4 a0, f32x4 a1, f32x4 b0, f32x4 b1, float rs) const {
; #pragma unroll
;         for (int i = 0; i < 4; ++i) {
;             const float x = a0[i] * rs, y = a1[i] * rs;
;             a0[i] = x * sigmoidf_(x) * (b0[i] * rs); a1[i] = y * sigmoidf_(y) * (b1[i] * rs);
;         }
;         *(u32x4*)(H + (size_t)row * DFF + lcol0) = pack8(a0, a1);
;     }
	v_cvt_pk_bf16_f32 v83, v88, v89
	v_cvt_pk_bf16_f32 v84, v90, v91
	v_cvt_pk_bf16_f32 v85, v92, v93
	v_lshl_add_u64 v[86:87], v[86:87], 0, v[116:117]
	flat_store_dwordx4 v[86:87], v[82:85]
	s_nop 1
	v_mul_f32_e32 v82, 0xbfb8aa3b, v78
	v_mul_f32_e32 v83, 0xbfb8aa3b, v79
	v_exp_f32_e32 v82, v82
	v_exp_f32_e32 v83, v83
	v_add_u32_e32 v84, s37, v153
	v_add_f32_e32 v82, 1.0, v82
	v_add_f32_e32 v83, 1.0, v83
	v_rcp_f32_e32 v82, v82
	v_rcp_f32_e32 v83, v83
	s_nop 0
	v_pk_mul_f32 v[78:79], v[78:79], v[82:83]
	s_nop 0
	v_pk_mul_f32 v[70:71], v[70:71], v[78:79]
	v_mul_f32_e32 v78, 0xbfb8aa3b, v74
	v_mul_f32_e32 v79, 0xbfb8aa3b, v75
	v_exp_f32_e32 v78, v78
	v_exp_f32_e32 v79, v79
	v_add_f32_e32 v78, 1.0, v78
	v_add_f32_e32 v79, 1.0, v79
	v_rcp_f32_e32 v78, v78
	v_rcp_f32_e32 v79, v79
	s_nop 0
	v_pk_mul_f32 v[74:75], v[74:75], v[78:79]
	s_nop 0
	v_pk_mul_f32 v[74:75], v[66:67], v[74:75]
	v_pk_mul_f32 v[66:67], v[80:81], v[150:151] op_sel_hi:[1,0]
	s_nop 0
	v_mul_f32_e32 v78, 0xbfb8aa3b, v66
	v_mul_f32_e32 v79, 0xbfb8aa3b, v67
	v_exp_f32_e32 v78, v78
	v_exp_f32_e32 v79, v79
	v_add_f32_e32 v78, 1.0, v78
	v_add_f32_e32 v79, 1.0, v79
	v_rcp_f32_e32 v78, v78
	v_rcp_f32_e32 v79, v79
	s_nop 0
	v_pk_mul_f32 v[66:67], v[66:67], v[78:79]
	s_nop 0
	v_pk_mul_f32 v[72:73], v[72:73], v[66:67]
	v_pk_mul_f32 v[66:67], v[76:77], v[150:151] op_sel_hi:[1,0]
	s_nop 0
	v_mul_f32_e32 v76, 0xbfb8aa3b, v66
	v_mul_f32_e32 v77, 0xbfb8aa3b, v67
	v_exp_f32_e32 v76, v76
	v_exp_f32_e32 v77, v77
	v_add_f32_e32 v76, 1.0, v76
	v_add_f32_e32 v77, 1.0, v77
	v_rcp_f32_e32 v76, v76
	v_rcp_f32_e32 v77, v77
	s_nop 0
	v_pk_mul_f32 v[66:67], v[66:67], v[76:77]
	s_nop 0
	v_pk_mul_f32 v[76:77], v[68:69], v[66:67]
	v_cvt_pk_bf16_f32 v66, v70, v71
	v_mad_i64_i32 v[70:71], s[14:15], v84, s17, v[114:115]
	v_cvt_pk_bf16_f32 v67, v72, v73
	v_cvt_pk_bf16_f32 v68, v74, v75
	v_cvt_pk_bf16_f32 v69, v76, v77
	v_lshl_add_u64 v[70:71], v[70:71], 0, v[116:117]
	flat_store_dwordx4 v[70:71], v[66:69]
	s_nop 1
	v_mul_f32_e32 v66, 0xbfb8aa3b, v62
	v_mul_f32_e32 v67, 0xbfb8aa3b, v63
	v_exp_f32_e32 v66, v66
	v_exp_f32_e32 v67, v67
	v_add_u32_e32 v68, 0x80, v140
	v_add_f32_e32 v66, 1.0, v66
	v_add_f32_e32 v67, 1.0, v67
	v_rcp_f32_e32 v66, v66
	v_rcp_f32_e32 v67, v67
	s_nop 0
	v_pk_mul_f32 v[62:63], v[62:63], v[66:67]
	s_nop 0
	v_pk_mul_f32 v[54:55], v[54:55], v[62:63]
	v_mul_f32_e32 v62, 0xbfb8aa3b, v58
	v_mul_f32_e32 v63, 0xbfb8aa3b, v59
	v_exp_f32_e32 v62, v62
	v_exp_f32_e32 v63, v63
	v_add_f32_e32 v62, 1.0, v62
	v_add_f32_e32 v63, 1.0, v63
	v_rcp_f32_e32 v62, v62
	v_rcp_f32_e32 v63, v63
	s_nop 0
	v_pk_mul_f32 v[58:59], v[58:59], v[62:63]
	s_nop 0
	v_pk_mul_f32 v[58:59], v[50:51], v[58:59]
	v_pk_mul_f32 v[50:51], v[64:65], v[148:149] op_sel_hi:[1,0]
	s_nop 0
	v_mul_f32_e32 v62, 0xbfb8aa3b, v50
	v_mul_f32_e32 v63, 0xbfb8aa3b, v51
	v_exp_f32_e32 v62, v62
	v_exp_f32_e32 v63, v63
	v_add_f32_e32 v62, 1.0, v62
	v_add_f32_e32 v63, 1.0, v63
	v_rcp_f32_e32 v62, v62
	v_rcp_f32_e32 v63, v63
	s_nop 0
	v_pk_mul_f32 v[50:51], v[50:51], v[62:63]
	s_nop 0
	v_pk_mul_f32 v[56:57], v[56:57], v[50:51]
	v_pk_mul_f32 v[50:51], v[60:61], v[148:149] op_sel_hi:[1,0]
	s_nop 0
	v_mul_f32_e32 v60, 0xbfb8aa3b, v50
	v_mul_f32_e32 v61, 0xbfb8aa3b, v51
	v_exp_f32_e32 v60, v60
	v_exp_f32_e32 v61, v61
	v_add_f32_e32 v60, 1.0, v60
	v_add_f32_e32 v61, 1.0, v61
	v_rcp_f32_e32 v60, v60
	v_rcp_f32_e32 v61, v61
	s_nop 0
	v_pk_mul_f32 v[50:51], v[50:51], v[60:61]
	s_nop 0
	v_pk_mul_f32 v[60:61], v[52:53], v[50:51]
	v_cvt_pk_bf16_f32 v50, v54, v55
	v_mad_i64_i32 v[54:55], s[14:15], v68, s17, v[114:115]
	v_cvt_pk_bf16_f32 v51, v56, v57
	v_cvt_pk_bf16_f32 v52, v58, v59
	v_cvt_pk_bf16_f32 v53, v60, v61
	v_lshl_add_u64 v[54:55], v[54:55], 0, v[116:117]
	flat_store_dwordx4 v[54:55], v[50:53]
	s_nop 1
	v_mul_f32_e32 v50, 0xbfb8aa3b, v46
	v_mul_f32_e32 v51, 0xbfb8aa3b, v47
	v_exp_f32_e32 v50, v50
	v_exp_f32_e32 v51, v51
	v_add_u32_e32 v52, 0x90, v140
	v_add_f32_e32 v50, 1.0, v50
	v_add_f32_e32 v51, 1.0, v51
	v_rcp_f32_e32 v50, v50
	v_rcp_f32_e32 v51, v51
	s_nop 0
	v_pk_mul_f32 v[46:47], v[46:47], v[50:51]
	s_nop 0
	v_pk_mul_f32 v[38:39], v[38:39], v[46:47]
	v_mul_f32_e32 v46, 0xbfb8aa3b, v42
	v_mul_f32_e32 v47, 0xbfb8aa3b, v43
	v_exp_f32_e32 v46, v46
	v_exp_f32_e32 v47, v47
	v_add_f32_e32 v46, 1.0, v46
	v_add_f32_e32 v47, 1.0, v47
	v_rcp_f32_e32 v46, v46
	v_rcp_f32_e32 v47, v47
	s_nop 0
	v_pk_mul_f32 v[42:43], v[42:43], v[46:47]
	s_nop 0
	v_pk_mul_f32 v[42:43], v[34:35], v[42:43]
	v_pk_mul_f32 v[34:35], v[48:49], v[146:147] op_sel_hi:[1,0]
	s_nop 0
	v_mul_f32_e32 v46, 0xbfb8aa3b, v34
	v_mul_f32_e32 v47, 0xbfb8aa3b, v35
; __device__ __forceinline__ u32x4 pack8(f32x4 a, f32x4 b) { u32x4 w; w.x = pk2(a.x, a.y); w.y = pk2(a.z, a.w); w.z = pk2(b.x, b.y); w.w = pk2(b.z, b.w); return w; }
; __device__ __forceinline__ float sigmoidf_(float v) { return __builtin_amdgcn_rcpf(1.f + __expf(-v)); }
; #define PG8_BAR __builtin_amdgcn_s_barrier()
;     __device__ __forceinline__ void apply2(int row, int lcol0, f32x4 a0, f32x4 a1, f32x4 b0, f32x4 b1, float rs) const {
; #pragma unroll
;         for (int i = 0; i < 4; ++i) {
;             const float x = a0[i] * rs, y = a1[i] * rs;
;             a0[i] = x * sigmoidf_(x) * (b0[i] * rs); a1[i] = y * sigmoidf_(y) * (b1[i] * rs);
;         }
;         *(u32x4*)(H + (size_t)row * DFF + lcol0) = pack8(a0, a1);
;     }
; template <class Epi, class Sched>
; __device__ __forceinline__ void gemm_phase(LAS unsigned char* lds, const Gemm g, const Sched& S, const Epi& E, const int tid) {
;     ...
;         E(acc, cur, wr, wc, fr, fq);
;         if (!has_next) break;
;         if (E.zero_after(cur))
; #pragma unroll
;         for (int a = 0; a < 2; ++a)
; #pragma unroll
;             for (int b = 0; b < 2; ++b)
; #pragma unroll
;                 for (int m = 0; m < 4; ++m)
; #pragma unroll
;                     for (int n = 0; n < 2; ++n) acc[a][b][m][n] = (f32x4){0.f, 0.f, 0.f, 0.f};
;         cur = nxt; cA = nA; cB = nB; ++ui;
;         if (wr == 1) PG8_BAR;
	v_exp_f32_e32 v46, v46
	v_exp_f32_e32 v47, v47
	v_add_f32_e32 v46, 1.0, v46
	v_add_f32_e32 v47, 1.0, v47
	v_rcp_f32_e32 v46, v46
	v_rcp_f32_e32 v47, v47
	s_nop 0
	v_pk_mul_f32 v[34:35], v[34:35], v[46:47]
	s_nop 0
	v_pk_mul_f32 v[40:41], v[40:41], v[34:35]
	v_pk_mul_f32 v[34:35], v[44:45], v[146:147] op_sel_hi:[1,0]
	s_nop 0
	v_mul_f32_e32 v44, 0xbfb8aa3b, v34
	v_mul_f32_e32 v45, 0xbfb8aa3b, v35
	v_exp_f32_e32 v44, v44
	v_exp_f32_e32 v45, v45
	v_add_f32_e32 v44, 1.0, v44
	v_add_f32_e32 v45, 1.0, v45
	v_rcp_f32_e32 v44, v44
	v_rcp_f32_e32 v45, v45
	s_nop 0
	v_pk_mul_f32 v[34:35], v[34:35], v[44:45]
	s_nop 0
	v_pk_mul_f32 v[44:45], v[36:37], v[34:35]
	v_cvt_pk_bf16_f32 v34, v38, v39
	v_mad_i64_i32 v[38:39], s[14:15], v52, s17, v[114:115]
	v_cvt_pk_bf16_f32 v35, v40, v41
	v_cvt_pk_bf16_f32 v36, v42, v43
	v_cvt_pk_bf16_f32 v37, v44, v45
	v_lshl_add_u64 v[38:39], v[38:39], 0, v[116:117]
	flat_store_dwordx4 v[38:39], v[34:37]
	s_nop 1
	v_mul_f32_e32 v34, 0xbfb8aa3b, v30
	v_mul_f32_e32 v35, 0xbfb8aa3b, v31
	v_exp_f32_e32 v34, v34
	v_exp_f32_e32 v35, v35
	v_add_u32_e32 v36, 0xa0, v140
	v_add_f32_e32 v34, 1.0, v34
	v_add_f32_e32 v35, 1.0, v35
	v_rcp_f32_e32 v34, v34
	v_rcp_f32_e32 v35, v35
	s_nop 0
	v_pk_mul_f32 v[30:31], v[30:31], v[34:35]
	s_nop 0
	v_pk_mul_f32 v[22:23], v[22:23], v[30:31]
	v_mul_f32_e32 v30, 0xbfb8aa3b, v26
	v_mul_f32_e32 v31, 0xbfb8aa3b, v27
	v_exp_f32_e32 v30, v30
	v_exp_f32_e32 v31, v31
	v_add_f32_e32 v30, 1.0, v30
	v_add_f32_e32 v31, 1.0, v31
	v_rcp_f32_e32 v30, v30
	v_rcp_f32_e32 v31, v31
	s_nop 0
	v_pk_mul_f32 v[26:27], v[26:27], v[30:31]
	s_nop 0
	v_pk_mul_f32 v[26:27], v[18:19], v[26:27]
	v_pk_mul_f32 v[18:19], v[32:33], v[144:145] op_sel_hi:[1,0]
	s_nop 0
	v_mul_f32_e32 v30, 0xbfb8aa3b, v18
	v_mul_f32_e32 v31, 0xbfb8aa3b, v19
	v_exp_f32_e32 v30, v30
	v_exp_f32_e32 v31, v31
	v_add_f32_e32 v30, 1.0, v30
	v_add_f32_e32 v31, 1.0, v31
	v_rcp_f32_e32 v30, v30
	v_rcp_f32_e32 v31, v31
	s_nop 0
	v_pk_mul_f32 v[18:19], v[18:19], v[30:31]
	s_nop 0
	v_pk_mul_f32 v[24:25], v[24:25], v[18:19]
	v_pk_mul_f32 v[18:19], v[28:29], v[144:145] op_sel_hi:[1,0]
	s_nop 0
	v_mul_f32_e32 v28, 0xbfb8aa3b, v18
	v_mul_f32_e32 v29, 0xbfb8aa3b, v19
	v_exp_f32_e32 v28, v28
	v_exp_f32_e32 v29, v29
	v_add_f32_e32 v28, 1.0, v28
	v_add_f32_e32 v29, 1.0, v29
	v_rcp_f32_e32 v28, v28
	v_rcp_f32_e32 v29, v29
	s_nop 0
	v_pk_mul_f32 v[18:19], v[18:19], v[28:29]
	s_nop 0
	v_pk_mul_f32 v[28:29], v[20:21], v[18:19]
	v_cvt_pk_bf16_f32 v18, v22, v23
	v_mad_i64_i32 v[22:23], s[14:15], v36, s17, v[114:115]
	v_cvt_pk_bf16_f32 v19, v24, v25
	v_cvt_pk_bf16_f32 v20, v26, v27
	v_cvt_pk_bf16_f32 v21, v28, v29
	v_lshl_add_u64 v[22:23], v[22:23], 0, v[116:117]
	flat_store_dwordx4 v[22:23], v[18:21]
	s_nop 1
	v_mul_f32_e32 v18, 0xbfb8aa3b, v14
	v_mul_f32_e32 v19, 0xbfb8aa3b, v15
	v_exp_f32_e32 v18, v18
	v_exp_f32_e32 v19, v19
	v_add_u32_e32 v20, 0xb0, v140
	v_add_f32_e32 v18, 1.0, v18
	v_add_f32_e32 v19, 1.0, v19
	v_rcp_f32_e32 v18, v18
	v_rcp_f32_e32 v19, v19
	s_nop 0
	v_pk_mul_f32 v[14:15], v[14:15], v[18:19]
	s_nop 0
	v_pk_mul_f32 v[6:7], v[6:7], v[14:15]
	v_mul_f32_e32 v14, 0xbfb8aa3b, v10
	v_mul_f32_e32 v15, 0xbfb8aa3b, v11
	v_exp_f32_e32 v14, v14
	v_exp_f32_e32 v15, v15
	v_add_f32_e32 v14, 1.0, v14
	v_add_f32_e32 v15, 1.0, v15
	v_rcp_f32_e32 v14, v14
	v_rcp_f32_e32 v15, v15
	s_nop 0
	v_pk_mul_f32 v[10:11], v[10:11], v[14:15]
	s_nop 0
	v_pk_mul_f32 v[10:11], v[2:3], v[10:11]
	v_pk_mul_f32 v[2:3], v[16:17], v[142:143] op_sel_hi:[1,0]
	s_nop 0
	v_mul_f32_e32 v14, 0xbfb8aa3b, v2
	v_mul_f32_e32 v15, 0xbfb8aa3b, v3
	v_exp_f32_e32 v14, v14
	v_exp_f32_e32 v15, v15
	v_add_f32_e32 v14, 1.0, v14
	v_add_f32_e32 v15, 1.0, v15
	v_rcp_f32_e32 v14, v14
	v_rcp_f32_e32 v15, v15
	s_nop 0
	v_pk_mul_f32 v[2:3], v[2:3], v[14:15]
	s_nop 0
	v_pk_mul_f32 v[8:9], v[8:9], v[2:3]
	v_pk_mul_f32 v[2:3], v[12:13], v[142:143] op_sel_hi:[1,0]
	s_nop 0
	v_mul_f32_e32 v12, 0xbfb8aa3b, v2
	v_mul_f32_e32 v13, 0xbfb8aa3b, v3
	v_exp_f32_e32 v12, v12
	v_exp_f32_e32 v13, v13
	v_add_f32_e32 v12, 1.0, v12
	v_add_f32_e32 v13, 1.0, v13
	v_rcp_f32_e32 v12, v12
	v_rcp_f32_e32 v13, v13
	s_nop 0
	v_pk_mul_f32 v[2:3], v[2:3], v[12:13]
	s_nop 0
	v_pk_mul_f32 v[12:13], v[4:5], v[2:3]
	v_cvt_pk_bf16_f32 v2, v6, v7
	v_mad_i64_i32 v[6:7], s[14:15], v20, s17, v[114:115]
	v_cvt_pk_bf16_f32 v3, v8, v9
	v_cvt_pk_bf16_f32 v4, v10, v11
	v_cvt_pk_bf16_f32 v5, v12, v13
	v_lshl_add_u64 v[6:7], v[6:7], 0, v[116:117]
	flat_store_dwordx4 v[6:7], v[2:5]
	s_cbranch_vccnz .LBB1_83
	s_andn2_b64 vcc, exec, s[4:5]
	s_cbranch_vccnz .LBB1_82
	s_barrier
	s_branch .LBB1_82
